# G4 epilogue (widened stores, global ops): the per-row rope-fetch waits are counted (vmcnt(2)) so a row no longer drains the previous row's store acks
# speedup vs baseline: 1.0049x; 1.0009x over previous
; #define ROPE_FETCH(ai_, m_) do { const int s_ = (u.pm * BM + (ai_) * HALF + wr * 64 + (m_) * 16 + fr) & 2047, pos_ = (wc & 1) ? (s_ & 63) : (s_ >> 6); \
;             n01 = *(const f32x4*)(rope + pos_ * 16 + 4 * fq); n23 = *(const f32x4*)(rope + pos_ * 16 + 4 * fq + 2); } while (0)
;     __device__ __forceinline__ void operator()(const f32x4 (&acc)[2][2][4][2], const Unit& u, int wr, int wc, int fr, int fq) const {
;     ...
;         if (do_rope) ROPE_FETCH(0, 0);
; #pragma unroll
;         for (int ai = 0; ai < 2; ++ai)
; #pragma unroll
;             for (int m = 0; m < 4; ++m) {
;                 const f32x4 c01 = n01, c23 = n23;
;                 if (do_rope && (ai * 4 + m) < 7) ROPE_FETCH((ai * 4 + m + 1) >> 2, (ai * 4 + m + 1) & 3);
.LBB0_239:
	v_mov_b64_e32 v[218:219], v[132:133]
	s_nop 1
	v_permlane16_swap_b32_e32 v216, v218
	v_permlane16_swap_b32_e32 v217, v219
	v_lshl_add_u64 v[220:221], v[130:131], 0, v[222:223]
	global_store_dwordx4 v[220:221], v[216:219], off
	s_waitcnt vmcnt(2) lgkmcnt(0)
	v_mov_b64_e32 v[118:119], v[126:127]
	v_mov_b64_e32 v[114:115], v[122:123]
	s_and_b64 vcc, exec, s[54:55]
	v_mov_b64_e32 v[120:121], v[128:129]
	v_mov_b64_e32 v[116:117], v[124:125]
	s_cbranch_vccnz .LBB0_241
	s_lshr_b32 s15, s29, 6
	s_add_i32 s15, s15, s67
	s_and_b32 s15, s15, 31
	v_mov_b32_e32 v0, s15
	v_cndmask_b32_e64 v0, v209, v0, s[38:39]
	v_lshlrev_b32_e32 v0, 7, v0
	v_lshl_add_u64 v[118:119], v[152:153], 0, v[0:1]
	global_load_dwordx4 v[114:117], v[118:119], off
	s_nop 0
	global_load_dwordx4 v[118:121], v[118:119], off offset:16

; #define ROPE_FETCH(ai_, m_) do { const int s_ = (u.pm * BM + (ai_) * HALF + wr * 64 + (m_) * 16 + fr) & 2047, pos_ = (wc & 1) ? (s_ & 63) : (s_ >> 6); \
;             n01 = *(const f32x4*)(rope + pos_ * 16 + 4 * fq); n23 = *(const f32x4*)(rope + pos_ * 16 + 4 * fq + 2); } while (0)
;     __device__ __forceinline__ void operator()(const f32x4 (&acc)[2][2][4][2], const Unit& u, int wr, int wc, int fr, int fq) const {
;     ...
;         if (do_rope) ROPE_FETCH(0, 0);
; #pragma unroll
;         for (int ai = 0; ai < 2; ++ai)
; #pragma unroll
;             for (int m = 0; m < 4; ++m) {
;                 const f32x4 c01 = n01, c23 = n23;
;                 if (do_rope && (ai * 4 + m) < 7) ROPE_FETCH((ai * 4 + m + 1) >> 2, (ai * 4 + m + 1) & 3);
.LBB0_277:
	v_mov_b64_e32 v[218:219], v[108:109]
	s_nop 1
	v_permlane16_swap_b32_e32 v216, v218
	v_permlane16_swap_b32_e32 v217, v219
	v_lshl_add_u64 v[220:221], v[106:107], 0, v[222:223]
	global_store_dwordx4 v[220:221], v[216:219], off
	s_waitcnt vmcnt(2) lgkmcnt(0)
	v_mov_b64_e32 v[102:103], v[118:119]
	v_mov_b64_e32 v[98:99], v[114:115]
	s_and_b64 vcc, exec, s[54:55]
	v_mov_b64_e32 v[104:105], v[120:121]
	v_mov_b64_e32 v[100:101], v[116:117]
	s_cbranch_vccnz .LBB0_279
	s_lshr_b32 s15, s29, 6
	s_add_i32 s15, s15, s67
	s_and_b32 s15, s15, 31
	v_mov_b32_e32 v0, s15
	v_cndmask_b32_e64 v0, v210, v0, s[38:39]
	v_lshlrev_b32_e32 v0, 7, v0
	v_lshl_add_u64 v[102:103], v[152:153], 0, v[0:1]
	global_load_dwordx4 v[98:101], v[102:103], off
	s_nop 0
	global_load_dwordx4 v[102:105], v[102:103], off offset:16

; #define ROPE_FETCH(ai_, m_) do { const int s_ = (u.pm * BM + (ai_) * HALF + wr * 64 + (m_) * 16 + fr) & 2047, pos_ = (wc & 1) ? (s_ & 63) : (s_ >> 6); \
;             n01 = *(const f32x4*)(rope + pos_ * 16 + 4 * fq); n23 = *(const f32x4*)(rope + pos_ * 16 + 4 * fq + 2); } while (0)
;     __device__ __forceinline__ void operator()(const f32x4 (&acc)[2][2][4][2], const Unit& u, int wr, int wc, int fr, int fq) const {
;     ...
;         if (do_rope) ROPE_FETCH(0, 0);
; #pragma unroll
;         for (int ai = 0; ai < 2; ++ai)
; #pragma unroll
;             for (int m = 0; m < 4; ++m) {
;                 const f32x4 c01 = n01, c23 = n23;
;                 if (do_rope && (ai * 4 + m) < 7) ROPE_FETCH((ai * 4 + m + 1) >> 2, (ai * 4 + m + 1) & 3);
.LBB0_315:
	v_mov_b64_e32 v[218:219], v[92:93]
	s_nop 1
	v_permlane16_swap_b32_e32 v216, v218
	v_permlane16_swap_b32_e32 v217, v219
	v_lshl_add_u64 v[220:221], v[90:91], 0, v[222:223]
	global_store_dwordx4 v[220:221], v[216:219], off
	s_waitcnt vmcnt(2) lgkmcnt(0)
	v_mov_b64_e32 v[86:87], v[102:103]
	v_mov_b64_e32 v[82:83], v[98:99]
	s_and_b64 vcc, exec, s[54:55]
	v_mov_b64_e32 v[88:89], v[104:105]
	v_mov_b64_e32 v[84:85], v[100:101]
	s_cbranch_vccnz .LBB0_317
	s_lshr_b32 s15, s29, 6
	v_readlane_b32 s96, v255, 14
	s_add_i32 s15, s15, s96
	s_and_b32 s15, s15, 31
	v_mov_b32_e32 v0, s15
	v_cndmask_b32_e64 v0, v151, v0, s[38:39]
	v_lshlrev_b32_e32 v0, 7, v0
	v_lshl_add_u64 v[86:87], v[152:153], 0, v[0:1]
	global_load_dwordx4 v[82:85], v[86:87], off
	s_nop 0
	global_load_dwordx4 v[86:89], v[86:87], off offset:16

; #define ROPE_FETCH(ai_, m_) do { const int s_ = (u.pm * BM + (ai_) * HALF + wr * 64 + (m_) * 16 + fr) & 2047, pos_ = (wc & 1) ? (s_ & 63) : (s_ >> 6); \
;             n01 = *(const f32x4*)(rope + pos_ * 16 + 4 * fq); n23 = *(const f32x4*)(rope + pos_ * 16 + 4 * fq + 2); } while (0)
;     __device__ __forceinline__ void operator()(const f32x4 (&acc)[2][2][4][2], const Unit& u, int wr, int wc, int fr, int fq) const {
;     ...
;         if (do_rope) ROPE_FETCH(0, 0);
; #pragma unroll
;         for (int ai = 0; ai < 2; ++ai)
; #pragma unroll
;             for (int m = 0; m < 4; ++m) {
;                 const f32x4 c01 = n01, c23 = n23;
;                 if (do_rope && (ai * 4 + m) < 7) ROPE_FETCH((ai * 4 + m + 1) >> 2, (ai * 4 + m + 1) & 3);
.LBB0_353:
	v_mov_b64_e32 v[218:219], v[76:77]
	s_nop 1
	v_permlane16_swap_b32_e32 v216, v218
	v_permlane16_swap_b32_e32 v217, v219
	v_lshl_add_u64 v[220:221], v[74:75], 0, v[222:223]
	global_store_dwordx4 v[220:221], v[216:219], off
	s_waitcnt vmcnt(2) lgkmcnt(0)
	v_mov_b64_e32 v[70:71], v[86:87]
	v_mov_b64_e32 v[66:67], v[82:83]
	s_and_b64 vcc, exec, s[54:55]
	v_mov_b64_e32 v[72:73], v[88:89]
	v_mov_b64_e32 v[68:69], v[84:85]
	s_cbranch_vccnz .LBB0_355
	s_lshr_b32 s3, s29, 6
	v_readlane_b32 s14, v255, 14
	s_add_i32 s3, s3, s14
	s_and_b32 s3, s3, 31
	v_mov_b32_e32 v0, s3
	v_cndmask_b32_e64 v0, v208, v0, s[38:39]
	v_lshlrev_b32_e32 v0, 7, v0
	v_lshl_add_u64 v[70:71], v[152:153], 0, v[0:1]
	global_load_dwordx4 v[66:69], v[70:71], off
	s_nop 0
	global_load_dwordx4 v[70:73], v[70:71], off offset:16

; #define ROPE_FETCH(ai_, m_) do { const int s_ = (u.pm * BM + (ai_) * HALF + wr * 64 + (m_) * 16 + fr) & 2047, pos_ = (wc & 1) ? (s_ & 63) : (s_ >> 6); \
;             n01 = *(const f32x4*)(rope + pos_ * 16 + 4 * fq); n23 = *(const f32x4*)(rope + pos_ * 16 + 4 * fq + 2); } while (0)
;     __device__ __forceinline__ void operator()(const f32x4 (&acc)[2][2][4][2], const Unit& u, int wr, int wc, int fr, int fq) const {
;     ...
;         if (do_rope) ROPE_FETCH(0, 0);
; #pragma unroll
;         for (int ai = 0; ai < 2; ++ai)
; #pragma unroll
;             for (int m = 0; m < 4; ++m) {
;                 const f32x4 c01 = n01, c23 = n23;
;                 if (do_rope && (ai * 4 + m) < 7) ROPE_FETCH((ai * 4 + m + 1) >> 2, (ai * 4 + m + 1) & 3);
.LBB0_391:
	v_mov_b64_e32 v[218:219], v[60:61]
	s_nop 1
	v_permlane16_swap_b32_e32 v216, v218
	v_permlane16_swap_b32_e32 v217, v219
	v_lshl_add_u64 v[220:221], v[58:59], 0, v[222:223]
	global_store_dwordx4 v[220:221], v[216:219], off
	s_waitcnt vmcnt(2) lgkmcnt(0)
	v_mov_b64_e32 v[54:55], v[70:71]
	v_mov_b64_e32 v[50:51], v[66:67]
	s_and_b64 vcc, exec, s[54:55]
	v_mov_b64_e32 v[56:57], v[72:73]
	v_mov_b64_e32 v[52:53], v[68:69]
	s_cbranch_vccnz .LBB0_393
	s_lshr_b32 s18, s29, 6
	v_readlane_b32 s19, v255, 14
	s_add_i32 s18, s18, s19
	s_and_b32 s18, s18, 31
	v_mov_b32_e32 v0, s18
	v_cndmask_b32_e64 v0, v209, v0, s[38:39]
	v_lshlrev_b32_e32 v0, 7, v0
	v_lshl_add_u64 v[54:55], v[152:153], 0, v[0:1]
	global_load_dwordx4 v[50:53], v[54:55], off
	s_nop 0
	global_load_dwordx4 v[54:57], v[54:55], off offset:16

; #define ROPE_FETCH(ai_, m_) do { const int s_ = (u.pm * BM + (ai_) * HALF + wr * 64 + (m_) * 16 + fr) & 2047, pos_ = (wc & 1) ? (s_ & 63) : (s_ >> 6); \
;             n01 = *(const f32x4*)(rope + pos_ * 16 + 4 * fq); n23 = *(const f32x4*)(rope + pos_ * 16 + 4 * fq + 2); } while (0)
;     __device__ __forceinline__ void operator()(const f32x4 (&acc)[2][2][4][2], const Unit& u, int wr, int wc, int fr, int fq) const {
;     ...
;         if (do_rope) ROPE_FETCH(0, 0);
; #pragma unroll
;         for (int ai = 0; ai < 2; ++ai)
; #pragma unroll
;             for (int m = 0; m < 4; ++m) {
;                 const f32x4 c01 = n01, c23 = n23;
;                 if (do_rope && (ai * 4 + m) < 7) ROPE_FETCH((ai * 4 + m + 1) >> 2, (ai * 4 + m + 1) & 3);
.LBB0_429:
	v_mov_b64_e32 v[218:219], v[44:45]
	s_nop 1
	v_permlane16_swap_b32_e32 v216, v218
	v_permlane16_swap_b32_e32 v217, v219
	v_lshl_add_u64 v[220:221], v[42:43], 0, v[222:223]
	global_store_dwordx4 v[220:221], v[216:219], off
	s_waitcnt vmcnt(2) lgkmcnt(0)
	v_mov_b64_e32 v[38:39], v[54:55]
	v_mov_b64_e32 v[34:35], v[50:51]
	s_and_b64 vcc, exec, s[54:55]
	v_mov_b64_e32 v[40:41], v[56:57]
	v_mov_b64_e32 v[36:37], v[52:53]
	s_cbranch_vccnz .LBB0_431
	s_lshr_b32 s15, s29, 6
	v_readlane_b32 s25, v255, 14
	s_add_i32 s15, s15, s25
	s_and_b32 s15, s15, 31
	v_mov_b32_e32 v0, s15
	v_cndmask_b32_e64 v0, v210, v0, s[38:39]
	v_lshlrev_b32_e32 v0, 7, v0
	v_lshl_add_u64 v[38:39], v[152:153], 0, v[0:1]
	global_load_dwordx4 v[34:37], v[38:39], off
	s_nop 0
	global_load_dwordx4 v[38:41], v[38:39], off offset:16

;     __device__ __forceinline__ void operator()(const f32x4 (&acc)[2][2][4][2], const Unit& u, int wr, int wc, int fr, int fq) const {
;     ...
;                     f32x4 v0 = acc[ai][bj][m][0], v1 = acc[ai][bj][m][1];
;                     const bool is_rope = (pn >= 2 && pn <= 6) || (pn == 9 && bj == 0);
;                     if (is_rope && lat) {
;                         const float cs[4] = {c01[0], c01[2], c23[0], c23[2]}, sn[4] = {c01[1], c01[3], c23[1], c23[3]};
; #pragma unroll
;                         for (int i = 0; i < 4; ++i) { const float x0 = v0[i], x1 = v1[i]; v0[i] = x0 * cs[i] - x1 * sn[i]; v1[i] = x1 * cs[i] + x0 * sn[i]; }
;                     }
.LBB0_467:
	v_mov_b64_e32 v[218:219], v[28:29]
	s_nop 1
	v_permlane16_swap_b32_e32 v216, v218
	v_permlane16_swap_b32_e32 v217, v219
	v_lshl_add_u64 v[220:221], v[26:27], 0, v[222:223]
	global_store_dwordx4 v[220:221], v[216:219], off
	s_and_b64 vcc, exec, s[46:47]
	s_cbranch_vccnz .LBB0_469
	s_waitcnt vmcnt(2) lgkmcnt(0)
	v_mul_f32_e32 v26, v12, v39
	v_mul_f32_e32 v28, v12, v38
	v_mov_b32_e32 v12, v17
	v_mov_b32_e32 v20, v35
	v_mov_b32_e32 v21, v37
	v_mul_f32_e32 v24, v16, v38
	v_mul_f32_e32 v30, v16, v39
	v_pk_mul_f32 v[32:33], v[12:13], v[40:41]
	v_mov_b32_e32 v16, v13
	v_mov_b32_e32 v18, v34
	v_mov_b32_e32 v19, v36
	v_pk_mul_f32 v[22:23], v[10:11], v[20:21]
	v_mov_b32_e32 v25, v32
	v_mov_b32_e32 v27, v33
	v_pk_mul_f32 v[12:13], v[16:17], v[40:41]
	v_pk_mul_f32 v[10:11], v[10:11], v[18:19]
	v_pk_fma_f32 v[18:19], v[14:15], v[18:19], v[22:23] neg_lo:[0,0,1] neg_hi:[0,0,1]
	v_pk_add_f32 v[22:23], v[24:25], v[26:27] neg_lo:[0,1] neg_hi:[0,1]
	v_mov_b32_e32 v31, v13
	v_mov_b32_e32 v29, v12
	v_pk_fma_f32 v[10:11], v[14:15], v[20:21], v[10:11]
	v_pk_add_f32 v[12:13], v[30:31], v[28:29]
	v_mov_b32_e32 v14, v18
	v_mov_b32_e32 v15, v19
	v_mov_b32_e32 v16, v22
	v_mov_b32_e32 v17, v23
